# M1 part A hand-written: all rows' c_q/c_kv/k_rope loads in flight, batched wave reductions, scalar row addressing
# speedup vs baseline: 1.0131x; 1.0040x over previous
;   __host__ __device__ __forceinline__ float* RS() const { return (float*)(wsl() + OFF_RS); }
;   __host__ __device__ __forceinline__ bf16_t* KR() const { return (bf16_t*)(wsl() + OFF_KR); }
;   __host__ __device__ __forceinline__ bf16_t* ACT() const { return (bf16_t*)(wsl() + OFF_ACT); }
; __device__ __forceinline__ float bf2f(bf16_t h) { return __uint_as_float(((uint32_t)h) << 16); }
; __device__ __forceinline__ int otid() { int t = threadIdx.x; asm volatile("" : "+v"(t)); return t; }
; __device__ __forceinline__ int obid() { int t = blockIdx.x; asm volatile("" : "+s"(t)); return t; }
; __device__ __forceinline__ void m1_phase(const Params& p, char* smem) {
;   const int tid = otid(), lane = tid & 63, w = tid >> 6, fr = lane & 15, fq = lane >> 4;
;   for (int row = obid() * 8 + w; row < NTOK; row += gridDim.x * 8) {
;     const bf16_t* pr = p.ACT() + (size_t)row * PW;
;     float sq = 0, skv = 0;
; #pragma unroll
;     for (int i = 0; i < 6; ++i) { float v = bf2f(pr[i * 64 + lane]); sq += v * v; }
; #pragma unroll
;     for (int i = 0; i < 4; ++i) { float v = bf2f(pr[384 + i * 64 + lane]); skv += v * v; }
;     sq = wave_sum(sq); skv = wave_sum(skv);
;     if (lane == 0) {
;       p.RS()[(size_t)row * 2] = rsqrtf(sq * (1.0f / 384.0f) + 1e-6f);
;       p.RS()[(size_t)row * 2 + 1] = rsqrtf(skv * (1.0f / 256.0f) + 1e-6f);
;     }
;     if (lane < 32) p.KR()[(size_t)row * 32 + lane] = pr[640 + lane];
;   }
.LBB0_756:
	s_andn2_b64 vcc, exec, s[2:3]
	s_cbranch_vccnz .LBB0_819
	v_readlane_b32 s2, v255, 58
	s_cmp_gt_i32 s2, 4
	s_mov_b64 s[2:3], -1
	s_cbranch_scc0 .LBB0_780
	v_mov_b32_e32 v8, v164
	s_mov_b32 s2, s82
	s_nop 0
	v_ashrrev_i32_e32 v18, 6, v8
	v_lshl_add_u32 v0, s2, 3, v18
	s_movk_i32 s2, 0x4200
	v_and_b32_e32 v10, 63, v8
	v_cmp_gt_i32_e32 vcc, s2, v0
	s_and_saveexec_b64 s[4:5], vcc
	s_cbranch_execz .LBB0_765
	s_waitcnt lgkmcnt(0)
	s_load_dwordx2 s[2:3], s[0:1], 0xf0
	v_readfirstlane_b32 s40, v0
	s_lshl_b32 s41, s80, 3
	v_lshlrev_b32_e32 v1, 2, v10
	v_xor_b32_e32 v2, 32, v231
	v_lshlrev_b32_e32 v2, 2, v2
	v_xor_b32_e32 v3, 16, v231
	v_lshlrev_b32_e32 v3, 2, v3
	v_xor_b32_e32 v4, 8, v231
	v_lshlrev_b32_e32 v4, 2, v4
	v_xor_b32_e32 v5, 4, v231
	v_lshlrev_b32_e32 v5, 2, v5
	v_xor_b32_e32 v6, 2, v231
	v_lshlrev_b32_e32 v6, 2, v6
	v_xor_b32_e32 v7, 1, v231
	v_lshlrev_b32_e32 v7, 2, v7
	s_waitcnt lgkmcnt(0)
	s_add_u32 s6, s2, 0x1128e000
	s_addc_u32 s7, s3, 0
	s_add_u32 s42, s2, 0x112af000
	s_addc_u32 s43, s3, 0
	s_add_u32 s44, s2, 0x7290000
	s_addc_u32 s45, s3, 0
	s_mov_b32 s50, s40
	s_cmpk_lt_u32 s50, 0x4200
	s_cbranch_scc0 .Lm1a_ld
	s_mul_i32 s46, s50, 0x1600
	s_add_u32 s46, s44, s46
	s_addc_u32 s47, s45, 0
	global_load_dword v32, v1, s[46:47]
	global_load_dword v33, v1, s[46:47] offset:256
	global_load_dword v34, v1, s[46:47] offset:512
	global_load_dword v35, v1, s[46:47] offset:768
	global_load_dword v36, v1, s[46:47] offset:1024
	global_load_dword v37, v1, s[46:47] offset:1280
	s_add_i32 s50, s50, s41
	s_cmpk_lt_u32 s50, 0x4200
	s_cbranch_scc0 .Lm1a_ld
	s_mul_i32 s46, s50, 0x1600
	s_add_u32 s46, s44, s46
	s_addc_u32 s47, s45, 0
	global_load_dword v38, v1, s[46:47]
	global_load_dword v39, v1, s[46:47] offset:256
	global_load_dword v40, v1, s[46:47] offset:512
	global_load_dword v41, v1, s[46:47] offset:768
	global_load_dword v42, v1, s[46:47] offset:1024
	global_load_dword v43, v1, s[46:47] offset:1280
	s_add_i32 s50, s50, s41
	s_cmpk_lt_u32 s50, 0x4200
	s_cbranch_scc0 .Lm1a_ld
	s_mul_i32 s46, s50, 0x1600
	s_add_u32 s46, s44, s46
	s_addc_u32 s47, s45, 0
	global_load_dword v44, v1, s[46:47]
	global_load_dword v45, v1, s[46:47] offset:256
	global_load_dword v46, v1, s[46:47] offset:512
	global_load_dword v47, v1, s[46:47] offset:768
	global_load_dword v48, v1, s[46:47] offset:1024
	global_load_dword v49, v1, s[46:47] offset:1280
	s_add_i32 s50, s50, s41
	s_cmpk_lt_u32 s50, 0x4200
	s_cbranch_scc0 .Lm1a_ld
	s_mul_i32 s46, s50, 0x1600
	s_add_u32 s46, s44, s46
	s_addc_u32 s47, s45, 0
	global_load_dword v50, v1, s[46:47]
	global_load_dword v51, v1, s[46:47] offset:256
	global_load_dword v52, v1, s[46:47] offset:512
	global_load_dword v53, v1, s[46:47] offset:768
	global_load_dword v54, v1, s[46:47] offset:1024
	global_load_dword v55, v1, s[46:47] offset:1280
	s_add_i32 s50, s50, s41
	s_cmpk_lt_u32 s50, 0x4200
	s_cbranch_scc0 .Lm1a_ld
	s_mul_i32 s46, s50, 0x1600
	s_add_u32 s46, s44, s46
	s_addc_u32 s47, s45, 0
	global_load_dword v56, v1, s[46:47]
	global_load_dword v57, v1, s[46:47] offset:256
	global_load_dword v58, v1, s[46:47] offset:512
	global_load_dword v59, v1, s[46:47] offset:768
	global_load_dword v60, v1, s[46:47] offset:1024
	global_load_dword v61, v1, s[46:47] offset:1280
	s_add_i32 s50, s50, s41
	s_cmpk_lt_u32 s50, 0x4200
	s_cbranch_scc0 .Lm1a_ld
	s_mul_i32 s46, s50, 0x1600
	s_add_u32 s46, s44, s46
	s_addc_u32 s47, s45, 0
	global_load_dword v62, v1, s[46:47]
	global_load_dword v63, v1, s[46:47] offset:256
	global_load_dword v64, v1, s[46:47] offset:512
	global_load_dword v65, v1, s[46:47] offset:768
	global_load_dword v66, v1, s[46:47] offset:1024
	global_load_dword v67, v1, s[46:47] offset:1280
	s_add_i32 s50, s50, s41
	s_cmpk_lt_u32 s50, 0x4200
	s_cbranch_scc0 .Lm1a_ld
	s_mul_i32 s46, s50, 0x1600
	s_add_u32 s46, s44, s46
	s_addc_u32 s47, s45, 0
	global_load_dword v68, v1, s[46:47]
	global_load_dword v69, v1, s[46:47] offset:256
	global_load_dword v70, v1, s[46:47] offset:512
	global_load_dword v71, v1, s[46:47] offset:768
	global_load_dword v72, v1, s[46:47] offset:1024
	global_load_dword v73, v1, s[46:47] offset:1280
	s_add_i32 s50, s50, s41
	s_cmpk_lt_u32 s50, 0x4200
	s_cbranch_scc0 .Lm1a_ld
	s_mul_i32 s46, s50, 0x1600
	s_add_u32 s46, s44, s46
	s_addc_u32 s47, s45, 0
	global_load_dword v74, v1, s[46:47]
	global_load_dword v75, v1, s[46:47] offset:256
	global_load_dword v76, v1, s[46:47] offset:512
	global_load_dword v77, v1, s[46:47] offset:768
	global_load_dword v78, v1, s[46:47] offset:1024
	global_load_dword v79, v1, s[46:47] offset:1280
	s_add_i32 s50, s50, s41
	s_cmpk_lt_u32 s50, 0x4200
	s_cbranch_scc0 .Lm1a_ld
	s_mul_i32 s46, s50, 0x1600
	s_add_u32 s46, s44, s46
	s_addc_u32 s47, s45, 0
	global_load_dword v80, v1, s[46:47]
	global_load_dword v81, v1, s[46:47] offset:256
	global_load_dword v82, v1, s[46:47] offset:512
	global_load_dword v83, v1, s[46:47] offset:768
	global_load_dword v84, v1, s[46:47] offset:1024
	global_load_dword v85, v1, s[46:47] offset:1280
	s_add_i32 s50, s50, s41
;   __host__ __device__ __forceinline__ bf16_t* ACT() const { return (bf16_t*)(wsl() + OFF_ACT); }
; __device__ __forceinline__ float bf2f(bf16_t h) { return __uint_as_float(((uint32_t)h) << 16); }
; __device__ __forceinline__ int obid() { int t = blockIdx.x; asm volatile("" : "+s"(t)); return t; }
; __device__ __forceinline__ void m1_phase(const Params& p, char* smem) {
;     ...
;   for (int row = obid() * 8 + w; row < NTOK; row += gridDim.x * 8) {
;     const bf16_t* pr = p.ACT() + (size_t)row * PW;
;     float sq = 0, skv = 0;
; #pragma unroll
;     for (int i = 0; i < 6; ++i) { float v = bf2f(pr[i * 64 + lane]); sq += v * v; }
; #pragma unroll
;     for (int i = 0; i < 4; ++i) { float v = bf2f(pr[384 + i * 64 + lane]); skv += v * v; }
;     sq = wave_sum(sq); skv = wave_sum(skv);
.Lm1a_ld:
	s_waitcnt vmcnt(0)
	v_lshlrev_b32_e32 v104, 16, v32
	v_and_b32_e32 v105, 0xffff0000, v32
	v_mul_f32_e32 v86, v104, v104
	v_fmac_f32_e32 v86, v105, v105
	v_lshlrev_b32_e32 v104, 16, v33
	v_and_b32_e32 v105, 0xffff0000, v33
	v_fmac_f32_e32 v86, v104, v104
	v_fmac_f32_e32 v86, v105, v105
	v_lshlrev_b32_e32 v104, 16, v34
	v_and_b32_e32 v105, 0xffff0000, v34
	v_fmac_f32_e32 v86, v104, v104
	v_fmac_f32_e32 v86, v105, v105
	v_lshlrev_b32_e32 v104, 16, v35
	v_and_b32_e32 v105, 0xffff0000, v35
	v_mul_f32_e32 v95, v104, v104
	v_fmac_f32_e32 v95, v105, v105
	v_lshlrev_b32_e32 v104, 16, v36
	v_and_b32_e32 v105, 0xffff0000, v36
	v_fmac_f32_e32 v95, v104, v104
	v_fmac_f32_e32 v95, v105, v105
	v_lshlrev_b32_e32 v104, 16, v38
	v_and_b32_e32 v105, 0xffff0000, v38
	v_mul_f32_e32 v87, v104, v104
	v_fmac_f32_e32 v87, v105, v105
	v_lshlrev_b32_e32 v104, 16, v39
	v_and_b32_e32 v105, 0xffff0000, v39
	v_fmac_f32_e32 v87, v104, v104
	v_fmac_f32_e32 v87, v105, v105
	v_lshlrev_b32_e32 v104, 16, v40
	v_and_b32_e32 v105, 0xffff0000, v40
	v_fmac_f32_e32 v87, v104, v104
	v_fmac_f32_e32 v87, v105, v105
	v_lshlrev_b32_e32 v104, 16, v41
	v_and_b32_e32 v105, 0xffff0000, v41
	v_mul_f32_e32 v96, v104, v104
	v_fmac_f32_e32 v96, v105, v105
	v_lshlrev_b32_e32 v104, 16, v42
	v_and_b32_e32 v105, 0xffff0000, v42
	v_fmac_f32_e32 v96, v104, v104
	v_fmac_f32_e32 v96, v105, v105
	v_lshlrev_b32_e32 v104, 16, v44
	v_and_b32_e32 v105, 0xffff0000, v44
	v_mul_f32_e32 v88, v104, v104
	v_fmac_f32_e32 v88, v105, v105
	v_lshlrev_b32_e32 v104, 16, v45
	v_and_b32_e32 v105, 0xffff0000, v45
	v_fmac_f32_e32 v88, v104, v104
	v_fmac_f32_e32 v88, v105, v105
	v_lshlrev_b32_e32 v104, 16, v46
	v_and_b32_e32 v105, 0xffff0000, v46
	v_fmac_f32_e32 v88, v104, v104
	v_fmac_f32_e32 v88, v105, v105
	v_lshlrev_b32_e32 v104, 16, v47
	v_and_b32_e32 v105, 0xffff0000, v47
	v_mul_f32_e32 v97, v104, v104
	v_fmac_f32_e32 v97, v105, v105
	v_lshlrev_b32_e32 v104, 16, v48
	v_and_b32_e32 v105, 0xffff0000, v48
	v_fmac_f32_e32 v97, v104, v104
	v_fmac_f32_e32 v97, v105, v105
	v_lshlrev_b32_e32 v104, 16, v50
	v_and_b32_e32 v105, 0xffff0000, v50
	v_mul_f32_e32 v89, v104, v104
	v_fmac_f32_e32 v89, v105, v105
	v_lshlrev_b32_e32 v104, 16, v51
	v_and_b32_e32 v105, 0xffff0000, v51
	v_fmac_f32_e32 v89, v104, v104
	v_fmac_f32_e32 v89, v105, v105
	v_lshlrev_b32_e32 v104, 16, v52
	v_and_b32_e32 v105, 0xffff0000, v52
	v_fmac_f32_e32 v89, v104, v104
	v_fmac_f32_e32 v89, v105, v105
	v_lshlrev_b32_e32 v104, 16, v53
	v_and_b32_e32 v105, 0xffff0000, v53
	v_mul_f32_e32 v98, v104, v104
	v_fmac_f32_e32 v98, v105, v105
	v_lshlrev_b32_e32 v104, 16, v54
	v_and_b32_e32 v105, 0xffff0000, v54
	v_fmac_f32_e32 v98, v104, v104
	v_fmac_f32_e32 v98, v105, v105
	v_lshlrev_b32_e32 v104, 16, v56
	v_and_b32_e32 v105, 0xffff0000, v56
	v_mul_f32_e32 v90, v104, v104
	v_fmac_f32_e32 v90, v105, v105
	v_lshlrev_b32_e32 v104, 16, v57
	v_and_b32_e32 v105, 0xffff0000, v57
	v_fmac_f32_e32 v90, v104, v104
	v_fmac_f32_e32 v90, v105, v105
	v_lshlrev_b32_e32 v104, 16, v58
	v_and_b32_e32 v105, 0xffff0000, v58
	v_fmac_f32_e32 v90, v104, v104
	v_fmac_f32_e32 v90, v105, v105
	v_lshlrev_b32_e32 v104, 16, v59
	v_and_b32_e32 v105, 0xffff0000, v59
	v_mul_f32_e32 v99, v104, v104
	v_fmac_f32_e32 v99, v105, v105
	v_lshlrev_b32_e32 v104, 16, v60
	v_and_b32_e32 v105, 0xffff0000, v60
	v_fmac_f32_e32 v99, v104, v104
	v_fmac_f32_e32 v99, v105, v105
	v_lshlrev_b32_e32 v104, 16, v62
	v_and_b32_e32 v105, 0xffff0000, v62
	v_mul_f32_e32 v91, v104, v104
	v_fmac_f32_e32 v91, v105, v105
	v_lshlrev_b32_e32 v104, 16, v63
	v_and_b32_e32 v105, 0xffff0000, v63
	v_fmac_f32_e32 v91, v104, v104
	v_fmac_f32_e32 v91, v105, v105
	v_lshlrev_b32_e32 v104, 16, v64
	v_and_b32_e32 v105, 0xffff0000, v64
	v_fmac_f32_e32 v91, v104, v104
	v_fmac_f32_e32 v91, v105, v105
	v_lshlrev_b32_e32 v104, 16, v65
	v_and_b32_e32 v105, 0xffff0000, v65
	v_mul_f32_e32 v100, v104, v104
	v_fmac_f32_e32 v100, v105, v105
	v_lshlrev_b32_e32 v104, 16, v66
	v_and_b32_e32 v105, 0xffff0000, v66
	v_fmac_f32_e32 v100, v104, v104
	v_fmac_f32_e32 v100, v105, v105
	v_lshlrev_b32_e32 v104, 16, v68
	v_and_b32_e32 v105, 0xffff0000, v68
	v_mul_f32_e32 v92, v104, v104
	v_fmac_f32_e32 v92, v105, v105
	v_lshlrev_b32_e32 v104, 16, v69
	v_and_b32_e32 v105, 0xffff0000, v69
	v_fmac_f32_e32 v92, v104, v104
	v_fmac_f32_e32 v92, v105, v105
	v_lshlrev_b32_e32 v104, 16, v70
	v_and_b32_e32 v105, 0xffff0000, v70
	v_fmac_f32_e32 v92, v104, v104
	v_fmac_f32_e32 v92, v105, v105
	v_lshlrev_b32_e32 v104, 16, v71
	v_and_b32_e32 v105, 0xffff0000, v71
	v_mul_f32_e32 v101, v104, v104
	v_fmac_f32_e32 v101, v105, v105
	v_lshlrev_b32_e32 v104, 16, v72
	v_and_b32_e32 v105, 0xffff0000, v72
	v_fmac_f32_e32 v101, v104, v104
	v_fmac_f32_e32 v101, v105, v105
	v_lshlrev_b32_e32 v104, 16, v74
	v_and_b32_e32 v105, 0xffff0000, v74
	v_mul_f32_e32 v93, v104, v104
	v_fmac_f32_e32 v93, v105, v105
	v_lshlrev_b32_e32 v104, 16, v75
	v_and_b32_e32 v105, 0xffff0000, v75
	v_fmac_f32_e32 v93, v104, v104
	v_fmac_f32_e32 v93, v105, v105
	v_lshlrev_b32_e32 v104, 16, v76
	v_and_b32_e32 v105, 0xffff0000, v76
	v_fmac_f32_e32 v93, v104, v104
	v_fmac_f32_e32 v93, v105, v105
	v_lshlrev_b32_e32 v104, 16, v77
	v_and_b32_e32 v105, 0xffff0000, v77
	v_mul_f32_e32 v102, v104, v104
	v_fmac_f32_e32 v102, v105, v105
	v_lshlrev_b32_e32 v104, 16, v78
	v_and_b32_e32 v105, 0xffff0000, v78
	v_fmac_f32_e32 v102, v104, v104
	v_fmac_f32_e32 v102, v105, v105
	v_lshlrev_b32_e32 v104, 16, v80
	v_and_b32_e32 v105, 0xffff0000, v80
	v_mul_f32_e32 v94, v104, v104
	v_fmac_f32_e32 v94, v105, v105
	v_lshlrev_b32_e32 v104, 16, v81
	v_and_b32_e32 v105, 0xffff0000, v81
	v_fmac_f32_e32 v94, v104, v104
	v_fmac_f32_e32 v94, v105, v105
	v_lshlrev_b32_e32 v104, 16, v82
	v_and_b32_e32 v105, 0xffff0000, v82
	v_fmac_f32_e32 v94, v104, v104
	v_fmac_f32_e32 v94, v105, v105
	v_lshlrev_b32_e32 v104, 16, v83
	v_and_b32_e32 v105, 0xffff0000, v83
	v_mul_f32_e32 v103, v104, v104
	v_fmac_f32_e32 v103, v105, v105
	v_lshlrev_b32_e32 v104, 16, v84
	v_and_b32_e32 v105, 0xffff0000, v84
	v_fmac_f32_e32 v103, v104, v104
	v_fmac_f32_e32 v103, v105, v105
	ds_bpermute_b32 v104, v2, v86
	ds_bpermute_b32 v105, v2, v87
	ds_bpermute_b32 v106, v2, v88
	ds_bpermute_b32 v107, v2, v89
	ds_bpermute_b32 v108, v2, v90
	ds_bpermute_b32 v109, v2, v91
	ds_bpermute_b32 v110, v2, v92
	ds_bpermute_b32 v111, v2, v93
	ds_bpermute_b32 v112, v2, v94
	s_waitcnt lgkmcnt(0)
; __device__ __forceinline__ float wave_sum(float v) {
; #pragma unroll
;   for (int o = 32; o >= 1; o >>= 1) v += __shfl_xor(v, o);
;   return v;
; }
; __device__ __forceinline__ void m1_phase(const Params& p, char* smem) {
;     ...
;     sq = wave_sum(sq); skv = wave_sum(skv);
	v_add_f32_e32 v86, v86, v104
	v_add_f32_e32 v87, v87, v105
	v_add_f32_e32 v88, v88, v106
	v_add_f32_e32 v89, v89, v107
	v_add_f32_e32 v90, v90, v108
	v_add_f32_e32 v91, v91, v109
	v_add_f32_e32 v92, v92, v110
	v_add_f32_e32 v93, v93, v111
	v_add_f32_e32 v94, v94, v112
	ds_bpermute_b32 v104, v2, v95
	ds_bpermute_b32 v105, v2, v96
	ds_bpermute_b32 v106, v2, v97
	ds_bpermute_b32 v107, v2, v98
	ds_bpermute_b32 v108, v2, v99
	ds_bpermute_b32 v109, v2, v100
	ds_bpermute_b32 v110, v2, v101
	ds_bpermute_b32 v111, v2, v102
	ds_bpermute_b32 v112, v2, v103
	s_waitcnt lgkmcnt(0)
	v_add_f32_e32 v95, v95, v104
	v_add_f32_e32 v96, v96, v105
	v_add_f32_e32 v97, v97, v106
	v_add_f32_e32 v98, v98, v107
	v_add_f32_e32 v99, v99, v108
	v_add_f32_e32 v100, v100, v109
	v_add_f32_e32 v101, v101, v110
	v_add_f32_e32 v102, v102, v111
	v_add_f32_e32 v103, v103, v112
	ds_bpermute_b32 v104, v3, v86
	ds_bpermute_b32 v105, v3, v87
	ds_bpermute_b32 v106, v3, v88
	ds_bpermute_b32 v107, v3, v89
	ds_bpermute_b32 v108, v3, v90
	ds_bpermute_b32 v109, v3, v91
	ds_bpermute_b32 v110, v3, v92
	ds_bpermute_b32 v111, v3, v93
	ds_bpermute_b32 v112, v3, v94
	s_waitcnt lgkmcnt(0)
	v_add_f32_e32 v86, v86, v104
	v_add_f32_e32 v87, v87, v105
	v_add_f32_e32 v88, v88, v106
	v_add_f32_e32 v89, v89, v107
	v_add_f32_e32 v90, v90, v108
	v_add_f32_e32 v91, v91, v109
	v_add_f32_e32 v92, v92, v110
	v_add_f32_e32 v93, v93, v111
	v_add_f32_e32 v94, v94, v112
	ds_bpermute_b32 v104, v3, v95
	ds_bpermute_b32 v105, v3, v96
	ds_bpermute_b32 v106, v3, v97
	ds_bpermute_b32 v107, v3, v98
	ds_bpermute_b32 v108, v3, v99
	ds_bpermute_b32 v109, v3, v100
	ds_bpermute_b32 v110, v3, v101
	ds_bpermute_b32 v111, v3, v102
	ds_bpermute_b32 v112, v3, v103
	s_waitcnt lgkmcnt(0)
	v_add_f32_e32 v95, v95, v104
	v_add_f32_e32 v96, v96, v105
	v_add_f32_e32 v97, v97, v106
	v_add_f32_e32 v98, v98, v107
	v_add_f32_e32 v99, v99, v108
	v_add_f32_e32 v100, v100, v109
	v_add_f32_e32 v101, v101, v110
	v_add_f32_e32 v102, v102, v111
	v_add_f32_e32 v103, v103, v112
	ds_bpermute_b32 v104, v4, v86
	ds_bpermute_b32 v105, v4, v87
	ds_bpermute_b32 v106, v4, v88
	ds_bpermute_b32 v107, v4, v89
	ds_bpermute_b32 v108, v4, v90
	ds_bpermute_b32 v109, v4, v91
	ds_bpermute_b32 v110, v4, v92
	ds_bpermute_b32 v111, v4, v93
	ds_bpermute_b32 v112, v4, v94
	s_waitcnt lgkmcnt(0)
	v_add_f32_e32 v86, v86, v104
	v_add_f32_e32 v87, v87, v105
	v_add_f32_e32 v88, v88, v106
	v_add_f32_e32 v89, v89, v107
	v_add_f32_e32 v90, v90, v108
	v_add_f32_e32 v91, v91, v109
	v_add_f32_e32 v92, v92, v110
	v_add_f32_e32 v93, v93, v111
	v_add_f32_e32 v94, v94, v112
	ds_bpermute_b32 v104, v4, v95
	ds_bpermute_b32 v105, v4, v96
	ds_bpermute_b32 v106, v4, v97
	ds_bpermute_b32 v107, v4, v98
	ds_bpermute_b32 v108, v4, v99
	ds_bpermute_b32 v109, v4, v100
	ds_bpermute_b32 v110, v4, v101
	ds_bpermute_b32 v111, v4, v102
	ds_bpermute_b32 v112, v4, v103
	s_waitcnt lgkmcnt(0)
	v_add_f32_e32 v95, v95, v104
	v_add_f32_e32 v96, v96, v105
	v_add_f32_e32 v97, v97, v106
	v_add_f32_e32 v98, v98, v107
	v_add_f32_e32 v99, v99, v108
	v_add_f32_e32 v100, v100, v109
	v_add_f32_e32 v101, v101, v110
	v_add_f32_e32 v102, v102, v111
	v_add_f32_e32 v103, v103, v112
	ds_bpermute_b32 v104, v5, v86
	ds_bpermute_b32 v105, v5, v87
	ds_bpermute_b32 v106, v5, v88
	ds_bpermute_b32 v107, v5, v89
	ds_bpermute_b32 v108, v5, v90
	ds_bpermute_b32 v109, v5, v91
	ds_bpermute_b32 v110, v5, v92
	ds_bpermute_b32 v111, v5, v93
	ds_bpermute_b32 v112, v5, v94
	s_waitcnt lgkmcnt(0)
	v_add_f32_e32 v86, v86, v104
	v_add_f32_e32 v87, v87, v105
	v_add_f32_e32 v88, v88, v106
	v_add_f32_e32 v89, v89, v107
	v_add_f32_e32 v90, v90, v108
	v_add_f32_e32 v91, v91, v109
	v_add_f32_e32 v92, v92, v110
	v_add_f32_e32 v93, v93, v111
	v_add_f32_e32 v94, v94, v112
	ds_bpermute_b32 v104, v5, v95
	ds_bpermute_b32 v105, v5, v96
	ds_bpermute_b32 v106, v5, v97
	ds_bpermute_b32 v107, v5, v98
	ds_bpermute_b32 v108, v5, v99
	ds_bpermute_b32 v109, v5, v100
	ds_bpermute_b32 v110, v5, v101
	ds_bpermute_b32 v111, v5, v102
	ds_bpermute_b32 v112, v5, v103
	s_waitcnt lgkmcnt(0)
	v_add_f32_e32 v95, v95, v104
	v_add_f32_e32 v96, v96, v105
	v_add_f32_e32 v97, v97, v106
	v_add_f32_e32 v98, v98, v107
	v_add_f32_e32 v99, v99, v108
	v_add_f32_e32 v100, v100, v109
	v_add_f32_e32 v101, v101, v110
	v_add_f32_e32 v102, v102, v111
	v_add_f32_e32 v103, v103, v112
	ds_bpermute_b32 v104, v6, v86
	ds_bpermute_b32 v105, v6, v87
	ds_bpermute_b32 v106, v6, v88
	ds_bpermute_b32 v107, v6, v89
	ds_bpermute_b32 v108, v6, v90
	ds_bpermute_b32 v109, v6, v91
	ds_bpermute_b32 v110, v6, v92
	ds_bpermute_b32 v111, v6, v93
	ds_bpermute_b32 v112, v6, v94
	s_waitcnt lgkmcnt(0)
	v_add_f32_e32 v86, v86, v104
	v_add_f32_e32 v87, v87, v105
	v_add_f32_e32 v88, v88, v106
	v_add_f32_e32 v89, v89, v107
	v_add_f32_e32 v90, v90, v108
	v_add_f32_e32 v91, v91, v109
	v_add_f32_e32 v92, v92, v110
	v_add_f32_e32 v93, v93, v111
	v_add_f32_e32 v94, v94, v112
	ds_bpermute_b32 v104, v6, v95
	ds_bpermute_b32 v105, v6, v96
	ds_bpermute_b32 v106, v6, v97
	ds_bpermute_b32 v107, v6, v98
	ds_bpermute_b32 v108, v6, v99
	ds_bpermute_b32 v109, v6, v100
	ds_bpermute_b32 v110, v6, v101
	ds_bpermute_b32 v111, v6, v102
	ds_bpermute_b32 v112, v6, v103
	s_waitcnt lgkmcnt(0)
	v_add_f32_e32 v95, v95, v104
	v_add_f32_e32 v96, v96, v105
	v_add_f32_e32 v97, v97, v106
	v_add_f32_e32 v98, v98, v107
	v_add_f32_e32 v99, v99, v108
	v_add_f32_e32 v100, v100, v109
	v_add_f32_e32 v101, v101, v110
	v_add_f32_e32 v102, v102, v111
	v_add_f32_e32 v103, v103, v112
	ds_bpermute_b32 v104, v7, v86
	ds_bpermute_b32 v105, v7, v87
	ds_bpermute_b32 v106, v7, v88
	ds_bpermute_b32 v107, v7, v89
	ds_bpermute_b32 v108, v7, v90
	ds_bpermute_b32 v109, v7, v91
	ds_bpermute_b32 v110, v7, v92
	ds_bpermute_b32 v111, v7, v93
	ds_bpermute_b32 v112, v7, v94
	s_waitcnt lgkmcnt(0)
;   __host__ __device__ __forceinline__ float* RS() const { return (float*)(wsl() + OFF_RS); }
; __device__ __forceinline__ void m1_phase(const Params& p, char* smem) {
;     ...
;     sq = wave_sum(sq); skv = wave_sum(skv);
;     if (lane == 0) {
;       p.RS()[(size_t)row * 2] = rsqrtf(sq * (1.0f / 384.0f) + 1e-6f);
;       p.RS()[(size_t)row * 2 + 1] = rsqrtf(skv * (1.0f / 256.0f) + 1e-6f);
;     }
	v_add_f32_e32 v86, v86, v104
	v_add_f32_e32 v87, v87, v105
	v_add_f32_e32 v88, v88, v106
	v_add_f32_e32 v89, v89, v107
	v_add_f32_e32 v90, v90, v108
	v_add_f32_e32 v91, v91, v109
	v_add_f32_e32 v92, v92, v110
	v_add_f32_e32 v93, v93, v111
	v_add_f32_e32 v94, v94, v112
	ds_bpermute_b32 v104, v7, v95
	ds_bpermute_b32 v105, v7, v96
	ds_bpermute_b32 v106, v7, v97
	ds_bpermute_b32 v107, v7, v98
	ds_bpermute_b32 v108, v7, v99
	ds_bpermute_b32 v109, v7, v100
	ds_bpermute_b32 v110, v7, v101
	ds_bpermute_b32 v111, v7, v102
	ds_bpermute_b32 v112, v7, v103
	s_waitcnt lgkmcnt(0)
	v_add_f32_e32 v95, v95, v104
	v_add_f32_e32 v96, v96, v105
	v_add_f32_e32 v97, v97, v106
	v_add_f32_e32 v98, v98, v107
	v_add_f32_e32 v99, v99, v108
	v_add_f32_e32 v100, v100, v109
	v_add_f32_e32 v101, v101, v110
	v_add_f32_e32 v102, v102, v111
	v_add_f32_e32 v103, v103, v112
	s_mov_b32 s46, 0x800000
	v_fmamk_f32 v86, v86, 0x3b2aaaab, v168
	v_mul_f32_e32 v104, 0x4b800000, v86
	v_cmp_gt_f32_e64 s[52:53], s46, v86
	s_nop 1
	v_cndmask_b32_e64 v86, v86, v104, s[52:53]
	v_rsq_f32_e32 v86, v86
	s_nop 0
	v_mul_f32_e32 v104, 0x45800000, v86
	v_cndmask_b32_e64 v86, v86, v104, s[52:53]
	v_fmamk_f32 v95, v95, 0x3b800000, v168
	v_mul_f32_e32 v104, 0x4b800000, v95
	v_cmp_gt_f32_e64 s[52:53], s46, v95
	s_nop 1
	v_cndmask_b32_e64 v95, v95, v104, s[52:53]
	v_rsq_f32_e32 v95, v95
	s_nop 0
	v_mul_f32_e32 v104, 0x45800000, v95
	v_cndmask_b32_e64 v95, v95, v104, s[52:53]
	v_fmamk_f32 v87, v87, 0x3b2aaaab, v168
	v_mul_f32_e32 v104, 0x4b800000, v87
	v_cmp_gt_f32_e64 s[52:53], s46, v87
	s_nop 1
	v_cndmask_b32_e64 v87, v87, v104, s[52:53]
	v_rsq_f32_e32 v87, v87
	s_nop 0
	v_mul_f32_e32 v104, 0x45800000, v87
	v_cndmask_b32_e64 v87, v87, v104, s[52:53]
	v_fmamk_f32 v96, v96, 0x3b800000, v168
	v_mul_f32_e32 v104, 0x4b800000, v96
	v_cmp_gt_f32_e64 s[52:53], s46, v96
	s_nop 1
	v_cndmask_b32_e64 v96, v96, v104, s[52:53]
	v_rsq_f32_e32 v96, v96
	s_nop 0
	v_mul_f32_e32 v104, 0x45800000, v96
	v_cndmask_b32_e64 v96, v96, v104, s[52:53]
	v_fmamk_f32 v88, v88, 0x3b2aaaab, v168
	v_mul_f32_e32 v104, 0x4b800000, v88
	v_cmp_gt_f32_e64 s[52:53], s46, v88
	s_nop 1
	v_cndmask_b32_e64 v88, v88, v104, s[52:53]
	v_rsq_f32_e32 v88, v88
	s_nop 0
	v_mul_f32_e32 v104, 0x45800000, v88
	v_cndmask_b32_e64 v88, v88, v104, s[52:53]
	v_fmamk_f32 v97, v97, 0x3b800000, v168
	v_mul_f32_e32 v104, 0x4b800000, v97
	v_cmp_gt_f32_e64 s[52:53], s46, v97
	s_nop 1
	v_cndmask_b32_e64 v97, v97, v104, s[52:53]
	v_rsq_f32_e32 v97, v97
	s_nop 0
	v_mul_f32_e32 v104, 0x45800000, v97
	v_cndmask_b32_e64 v97, v97, v104, s[52:53]
	v_fmamk_f32 v89, v89, 0x3b2aaaab, v168
	v_mul_f32_e32 v104, 0x4b800000, v89
	v_cmp_gt_f32_e64 s[52:53], s46, v89
	s_nop 1
	v_cndmask_b32_e64 v89, v89, v104, s[52:53]
	v_rsq_f32_e32 v89, v89
	s_nop 0
	v_mul_f32_e32 v104, 0x45800000, v89
	v_cndmask_b32_e64 v89, v89, v104, s[52:53]
	v_fmamk_f32 v98, v98, 0x3b800000, v168
	v_mul_f32_e32 v104, 0x4b800000, v98
	v_cmp_gt_f32_e64 s[52:53], s46, v98
	s_nop 1
	v_cndmask_b32_e64 v98, v98, v104, s[52:53]
	v_rsq_f32_e32 v98, v98
	s_nop 0
	v_mul_f32_e32 v104, 0x45800000, v98
	v_cndmask_b32_e64 v98, v98, v104, s[52:53]
	v_fmamk_f32 v90, v90, 0x3b2aaaab, v168
	v_mul_f32_e32 v104, 0x4b800000, v90
	v_cmp_gt_f32_e64 s[52:53], s46, v90
	s_nop 1
	v_cndmask_b32_e64 v90, v90, v104, s[52:53]
	v_rsq_f32_e32 v90, v90
	s_nop 0
	v_mul_f32_e32 v104, 0x45800000, v90
	v_cndmask_b32_e64 v90, v90, v104, s[52:53]
	v_fmamk_f32 v99, v99, 0x3b800000, v168
	v_mul_f32_e32 v104, 0x4b800000, v99
	v_cmp_gt_f32_e64 s[52:53], s46, v99
	s_nop 1
	v_cndmask_b32_e64 v99, v99, v104, s[52:53]
	v_rsq_f32_e32 v99, v99
	s_nop 0
	v_mul_f32_e32 v104, 0x45800000, v99
	v_cndmask_b32_e64 v99, v99, v104, s[52:53]
	v_fmamk_f32 v91, v91, 0x3b2aaaab, v168
	v_mul_f32_e32 v104, 0x4b800000, v91
	v_cmp_gt_f32_e64 s[52:53], s46, v91
	s_nop 1
	v_cndmask_b32_e64 v91, v91, v104, s[52:53]
	v_rsq_f32_e32 v91, v91
	s_nop 0
	v_mul_f32_e32 v104, 0x45800000, v91
	v_cndmask_b32_e64 v91, v91, v104, s[52:53]
	v_fmamk_f32 v100, v100, 0x3b800000, v168
	v_mul_f32_e32 v104, 0x4b800000, v100
	v_cmp_gt_f32_e64 s[52:53], s46, v100
	s_nop 1
	v_cndmask_b32_e64 v100, v100, v104, s[52:53]
	v_rsq_f32_e32 v100, v100
	s_nop 0
	v_mul_f32_e32 v104, 0x45800000, v100
	v_cndmask_b32_e64 v100, v100, v104, s[52:53]
	v_fmamk_f32 v92, v92, 0x3b2aaaab, v168
	v_mul_f32_e32 v104, 0x4b800000, v92
	v_cmp_gt_f32_e64 s[52:53], s46, v92
	s_nop 1
	v_cndmask_b32_e64 v92, v92, v104, s[52:53]
	v_rsq_f32_e32 v92, v92
	s_nop 0
	v_mul_f32_e32 v104, 0x45800000, v92
	v_cndmask_b32_e64 v92, v92, v104, s[52:53]
	v_fmamk_f32 v101, v101, 0x3b800000, v168
	v_mul_f32_e32 v104, 0x4b800000, v101
	v_cmp_gt_f32_e64 s[52:53], s46, v101
	s_nop 1
	v_cndmask_b32_e64 v101, v101, v104, s[52:53]
	v_rsq_f32_e32 v101, v101
	s_nop 0
	v_mul_f32_e32 v104, 0x45800000, v101
	v_cndmask_b32_e64 v101, v101, v104, s[52:53]
	v_fmamk_f32 v93, v93, 0x3b2aaaab, v168
	v_mul_f32_e32 v104, 0x4b800000, v93
	v_cmp_gt_f32_e64 s[52:53], s46, v93
	s_nop 1
	v_cndmask_b32_e64 v93, v93, v104, s[52:53]
	v_rsq_f32_e32 v93, v93
	s_nop 0
	v_mul_f32_e32 v104, 0x45800000, v93
	v_cndmask_b32_e64 v93, v93, v104, s[52:53]
	v_fmamk_f32 v102, v102, 0x3b800000, v168
	v_mul_f32_e32 v104, 0x4b800000, v102
	v_cmp_gt_f32_e64 s[52:53], s46, v102
	s_nop 1
	v_cndmask_b32_e64 v102, v102, v104, s[52:53]
	v_rsq_f32_e32 v102, v102
	s_nop 0
	v_mul_f32_e32 v104, 0x45800000, v102
	v_cndmask_b32_e64 v102, v102, v104, s[52:53]
	v_fmamk_f32 v94, v94, 0x3b2aaaab, v168
	v_mul_f32_e32 v104, 0x4b800000, v94
	v_cmp_gt_f32_e64 s[52:53], s46, v94
	s_nop 1
	v_cndmask_b32_e64 v94, v94, v104, s[52:53]
	v_rsq_f32_e32 v94, v94
	s_nop 0
	v_mul_f32_e32 v104, 0x45800000, v94
	v_cndmask_b32_e64 v94, v94, v104, s[52:53]
	v_fmamk_f32 v103, v103, 0x3b800000, v168
	v_mul_f32_e32 v104, 0x4b800000, v103
	v_cmp_gt_f32_e64 s[52:53], s46, v103
	s_nop 1
	v_cndmask_b32_e64 v103, v103, v104, s[52:53]
	v_rsq_f32_e32 v103, v103
	s_nop 0
	v_mul_f32_e32 v104, 0x45800000, v103
	v_cndmask_b32_e64 v103, v103, v104, s[52:53]
	s_mov_b64 s[48:49], exec
	s_mov_b32 s50, s40
	v_mov_b32_e32 v122, 0
	s_cmpk_lt_u32 s50, 0x4200
	s_cbranch_scc0 .Lm1a_st
;   __host__ __device__ __forceinline__ float* RS() const { return (float*)(wsl() + OFF_RS); }
;   __host__ __device__ __forceinline__ bf16_t* KR() const { return (bf16_t*)(wsl() + OFF_KR); }
; __device__ __forceinline__ void m1_phase(const Params& p, char* smem) {
;     ...
;     if (lane == 0) {
;       p.RS()[(size_t)row * 2] = rsqrtf(sq * (1.0f / 384.0f) + 1e-6f);
;       p.RS()[(size_t)row * 2 + 1] = rsqrtf(skv * (1.0f / 256.0f) + 1e-6f);
;     }
;     if (lane < 32) p.KR()[(size_t)row * 32 + lane] = pr[640 + lane];
;   }
	v_mov_b32_e32 v104, v86
	v_mov_b32_e32 v105, v95
	s_lshl_b32 s46, s50, 3
	s_add_u32 s46, s6, s46
	s_addc_u32 s47, s7, 0
	s_mov_b64 exec, 1
	global_store_dwordx2 v122, v[104:105], s[46:47]
	s_lshl_b32 s46, s50, 6
	s_add_u32 s46, s42, s46
	s_addc_u32 s47, s43, 0
	s_mov_b64 exec, 0xffff
	global_store_dword v1, v37, s[46:47]
	s_mov_b64 exec, s[48:49]
	s_add_i32 s50, s50, s41
	s_cmpk_lt_u32 s50, 0x4200
	s_cbranch_scc0 .Lm1a_st
	v_mov_b32_e32 v104, v87
	v_mov_b32_e32 v105, v96
	s_lshl_b32 s46, s50, 3
	s_add_u32 s46, s6, s46
	s_addc_u32 s47, s7, 0
	s_mov_b64 exec, 1
	global_store_dwordx2 v122, v[104:105], s[46:47]
	s_lshl_b32 s46, s50, 6
	s_add_u32 s46, s42, s46
	s_addc_u32 s47, s43, 0
	s_mov_b64 exec, 0xffff
	global_store_dword v1, v43, s[46:47]
	s_mov_b64 exec, s[48:49]
	s_add_i32 s50, s50, s41
	s_cmpk_lt_u32 s50, 0x4200
	s_cbranch_scc0 .Lm1a_st
	v_mov_b32_e32 v104, v88
	v_mov_b32_e32 v105, v97
	s_lshl_b32 s46, s50, 3
	s_add_u32 s46, s6, s46
	s_addc_u32 s47, s7, 0
	s_mov_b64 exec, 1
	global_store_dwordx2 v122, v[104:105], s[46:47]
	s_lshl_b32 s46, s50, 6
	s_add_u32 s46, s42, s46
	s_addc_u32 s47, s43, 0
	s_mov_b64 exec, 0xffff
	global_store_dword v1, v49, s[46:47]
	s_mov_b64 exec, s[48:49]
	s_add_i32 s50, s50, s41
	s_cmpk_lt_u32 s50, 0x4200
	s_cbranch_scc0 .Lm1a_st
	v_mov_b32_e32 v104, v89
	v_mov_b32_e32 v105, v98
	s_lshl_b32 s46, s50, 3
	s_add_u32 s46, s6, s46
	s_addc_u32 s47, s7, 0
	s_mov_b64 exec, 1
	global_store_dwordx2 v122, v[104:105], s[46:47]
	s_lshl_b32 s46, s50, 6
	s_add_u32 s46, s42, s46
	s_addc_u32 s47, s43, 0
	s_mov_b64 exec, 0xffff
	global_store_dword v1, v55, s[46:47]
	s_mov_b64 exec, s[48:49]
	s_add_i32 s50, s50, s41
	s_cmpk_lt_u32 s50, 0x4200
	s_cbranch_scc0 .Lm1a_st
	v_mov_b32_e32 v104, v90
	v_mov_b32_e32 v105, v99
	s_lshl_b32 s46, s50, 3
	s_add_u32 s46, s6, s46
	s_addc_u32 s47, s7, 0
	s_mov_b64 exec, 1
	global_store_dwordx2 v122, v[104:105], s[46:47]
	s_lshl_b32 s46, s50, 6
	s_add_u32 s46, s42, s46
	s_addc_u32 s47, s43, 0
	s_mov_b64 exec, 0xffff
	global_store_dword v1, v61, s[46:47]
	s_mov_b64 exec, s[48:49]
	s_add_i32 s50, s50, s41
	s_cmpk_lt_u32 s50, 0x4200
	s_cbranch_scc0 .Lm1a_st
	v_mov_b32_e32 v104, v91
	v_mov_b32_e32 v105, v100
	s_lshl_b32 s46, s50, 3
	s_add_u32 s46, s6, s46
	s_addc_u32 s47, s7, 0
	s_mov_b64 exec, 1
	global_store_dwordx2 v122, v[104:105], s[46:47]
	s_lshl_b32 s46, s50, 6
	s_add_u32 s46, s42, s46
	s_addc_u32 s47, s43, 0
	s_mov_b64 exec, 0xffff
	global_store_dword v1, v67, s[46:47]
	s_mov_b64 exec, s[48:49]
	s_add_i32 s50, s50, s41
	s_cmpk_lt_u32 s50, 0x4200
	s_cbranch_scc0 .Lm1a_st
	v_mov_b32_e32 v104, v92
	v_mov_b32_e32 v105, v101
	s_lshl_b32 s46, s50, 3
	s_add_u32 s46, s6, s46
	s_addc_u32 s47, s7, 0
	s_mov_b64 exec, 1
	global_store_dwordx2 v122, v[104:105], s[46:47]
	s_lshl_b32 s46, s50, 6
	s_add_u32 s46, s42, s46
	s_addc_u32 s47, s43, 0
	s_mov_b64 exec, 0xffff
	global_store_dword v1, v73, s[46:47]
	s_mov_b64 exec, s[48:49]
	s_add_i32 s50, s50, s41
	s_cmpk_lt_u32 s50, 0x4200
	s_cbranch_scc0 .Lm1a_st
	v_mov_b32_e32 v104, v93
	v_mov_b32_e32 v105, v102
	s_lshl_b32 s46, s50, 3
	s_add_u32 s46, s6, s46
	s_addc_u32 s47, s7, 0
	s_mov_b64 exec, 1
	global_store_dwordx2 v122, v[104:105], s[46:47]
	s_lshl_b32 s46, s50, 6
	s_add_u32 s46, s42, s46
	s_addc_u32 s47, s43, 0
	s_mov_b64 exec, 0xffff
	global_store_dword v1, v79, s[46:47]
	s_mov_b64 exec, s[48:49]
	s_add_i32 s50, s50, s41
	s_cmpk_lt_u32 s50, 0x4200
	s_cbranch_scc0 .Lm1a_st
	v_mov_b32_e32 v104, v94
	v_mov_b32_e32 v105, v103
	s_lshl_b32 s46, s50, 3
	s_add_u32 s46, s6, s46
	s_addc_u32 s47, s7, 0
	s_mov_b64 exec, 1
	global_store_dwordx2 v122, v[104:105], s[46:47]
	s_lshl_b32 s46, s50, 6
	s_add_u32 s46, s42, s46
	s_addc_u32 s47, s43, 0
	s_mov_b64 exec, 0xffff
	global_store_dword v1, v85, s[46:47]
	s_mov_b64 exec, s[48:49]
	s_add_i32 s50, s50, s41
.Lm1a_st:
	s_mov_b64 exec, s[48:49]
